# scan consumer: y of a chunk's last step taken from the next chunk's step 0 (its (nk, r_prev) pair already carries that r): per-chunk tail loses the separate r load, 3 VALU and a write
# baseline (speedup 1.0000x reference)
; #define LAS __attribute__((address_space(3)))
; #define RW_LDS_WAIT(X) asm volatile("s_waitcnt lgkmcnt(0)" : "+v"(nk##X), "+v"(dd##X), "+v"(bb##X), "+v"(kp##X), "+v"(rr##X), "+v"(vv##X) :: "memory")
; DI void rwkv_scan_phase(int wv, const Params& P, LAS unsigned char* lds) {
;     ...
;             const int cg = lane & 15, rloc = wave * 4 + (lane >> 4);
;             f32x4 S = (f32x4){0.f, 0.f, 0.f, 0.f};
;             __syncthreads();
;             __builtin_amdgcn_s_setprio(3);
; #pragma unroll 1
;             for (int ck = 0; ck < nck; ++ck) { const int buf = ck & 1;
;                 const LAS float* sb = stg + buf * RW_T * 5 * 64 + 4 * cg; const LAS float* vb = vst + buf * RW_T * 8 + rloc; LAS float* yb = ybuf + buf * RW_T * 128 + wave * 64 + lane;
;                 const unsigned sba = (unsigned)(size_t)sb, vba = (unsigned)(size_t)vb;
;                 f32x4 nkA, ddA, bbA, kpA, rrA, nkB, ddB, bbB, kpB, rrB; float vvA, vvB;
;     ...
;                 f32x2 yacc = (f32x2){0.f, 0.f};
;                 unsigned sbt = sba, vbt = vba; LAS float* ybt = yb;
;                 RW_LDS_LOAD(A, 0); RW_LDS_WAIT(A);
; #pragma unroll 1
;                 for (int tt = 0; tt < RW_T; tt += 16) { sbt = sba + (unsigned)tt * 1280u; vbt = vba + (unsigned)tt * 32u; ybt = yb + tt * 128;
;                     RW_LDS_LOAD(B, 1); RW_STEP(A, 0); RW_LDS_WAIT(B);
;                     RW_LDS_LOAD(A, 2); RW_STEP(B, 1); RW_LDS_WAIT(A);
;                     RW_LDS_LOAD(B, 3); RW_STEP(A, 2); RW_LDS_WAIT(B);
;                     RW_LDS_LOAD(A, 4); RW_STEP(B, 3); RW_LDS_WAIT(A);
.LBB0_3177:
	s_waitcnt lgkmcnt(0)
	s_barrier
	s_and_saveexec_b64 s[20:21], s[2:3]
	s_xor_b64 s[20:21], exec, s[20:21]
	s_cbranch_execz .LBB0_3185
	s_barrier
	s_setprio 3
	v_add_u32_e32 v42, 0xfffec000, v63
	v_mov_b32_e32 v58, 0
	v_mov_b32_e32 v59, 0
	v_lshl_add_u32 v42, v42, 6, v45
	v_mov_b32_e32 v60, 0
	v_mov_b32_e32 v61, 0
	v_add_u32_e32 v42, 0x400, v42
	v_add_u32_e32 v62, 0x3800, v66
	s_mov_b32 s47, 0
	s_mov_b32 s42, 0
	s_lshl_b32 s40, s47, 4
	s_and_b32 s40, s40, 16
	s_mul_i32 s41, s40, 0xc00
	v_add_u32_e32 v74, s41, v45
	v_add_u32_e32 v73, v74, v45
	v_add_u32_e32 v75, s41, v42
	v_add_u32_e32 v67, s42, v62
	s_lshl_b32 s41, s40, 4
	s_add_i32 s41, s41, 0x1e000
	v_add_u32_e32 v40, s41, v45
	v_add_u32_e32 v72, 0x4000, v62
	ds_read_b128 v[0:3], v73
	ds_read_b128 v[16:19], v73 offset:16
	ds_read_b128 v[4:7], v74 offset:512
	ds_read_b128 v[12:15], v75
	ds_read_b128 v[8:11], v74 offset:768
	ds_read_b128 v[20:23], v73 offset:3072
	ds_read_b128 v[36:39], v73 offset:3088
	ds_read_b128 v[24:27], v74 offset:3584
	ds_read_b128 v[32:35], v75 offset:3072
	ds_read_b128 v[28:31], v74 offset:3840
.Lscan_chunk:
	s_waitcnt lgkmcnt(5)
	v_pk_mul_f32 v[0:1], v[58:59], v[0:1] op_sel_hi:[0,1]
	v_pk_fma_f32 v[0:1], v[58:59], v[2:3], v[0:1] op_sel:[1,0,0] op_sel_hi:[1,1,1]
	v_pk_fma_f32 v[0:1], v[60:61], v[16:17], v[0:1] op_sel_hi:[0,1,1]
	v_pk_fma_f32 v[0:1], v[60:61], v[18:19], v[0:1] op_sel:[1,0,0] op_sel_hi:[1,1,1]
	v_pk_fma_f32 v[12:13], v[58:59], v[4:5], v[12:13]
	v_pk_fma_f32 v[14:15], v[60:61], v[6:7], v[14:15]
	v_add_f32_dpp v0, v0, v0 quad_perm:[1,0,3,2] row_mask:0xf bank_mask:0xf bound_ctrl:1
	ds_read_b128 v[46:49], v73 offset:6144
	ds_read_b128 v[76:79], v73 offset:6160
	v_add_f32_dpp v0, v0, v0 quad_perm:[2,3,0,1] row_mask:0xf bank_mask:0xf bound_ctrl:1
	ds_read_b128 v[50:53], v74 offset:6656
	ds_read_b128 v[68:71], v75 offset:6144
	v_add_f32_dpp v0, v0, v0 row_half_mirror row_mask:0xf bank_mask:0xf bound_ctrl:1
	ds_read_b128 v[54:57], v74 offset:6912
	ds_write_b32 v72, v1 offset:7680
	v_add_f32_dpp v0, v0, v0 row_mirror row_mask:0xf bank_mask:0xf bound_ctrl:1
	v_pk_fma_f32 v[58:59], v[8:9], v[0:1], v[12:13] op_sel_hi:[1,0,1]
	v_pk_fma_f32 v[60:61], v[10:11], v[0:1], v[14:15] op_sel_hi:[1,0,1]
	v_mov_b32_e32 v72, v67
	s_waitcnt lgkmcnt(6)
	v_pk_mul_f32 v[20:21], v[58:59], v[20:21] op_sel_hi:[0,1]
	v_pk_fma_f32 v[20:21], v[58:59], v[22:23], v[20:21] op_sel:[1,0,0] op_sel_hi:[1,1,1]
	v_pk_fma_f32 v[20:21], v[60:61], v[36:37], v[20:21] op_sel_hi:[0,1,1]
	v_pk_fma_f32 v[20:21], v[60:61], v[38:39], v[20:21] op_sel:[1,0,0] op_sel_hi:[1,1,1]
	v_pk_fma_f32 v[32:33], v[58:59], v[24:25], v[32:33]
	v_pk_fma_f32 v[34:35], v[60:61], v[26:27], v[34:35]
	v_add_f32_dpp v20, v20, v20 quad_perm:[1,0,3,2] row_mask:0xf bank_mask:0xf bound_ctrl:1
	ds_read_b128 v[0:3], v73 offset:9216
	ds_read_b128 v[16:19], v73 offset:9232
	v_add_f32_dpp v20, v20, v20 quad_perm:[2,3,0,1] row_mask:0xf bank_mask:0xf bound_ctrl:1
	ds_read_b128 v[4:7], v74 offset:9728
	ds_read_b128 v[12:15], v75 offset:9216
	v_add_f32_dpp v20, v20, v20 row_half_mirror row_mask:0xf bank_mask:0xf bound_ctrl:1
	ds_read_b128 v[8:11], v74 offset:9984
	ds_write_b32 v72, v21
	v_add_f32_dpp v20, v20, v20 row_mirror row_mask:0xf bank_mask:0xf bound_ctrl:1
	v_pk_fma_f32 v[58:59], v[28:29], v[20:21], v[32:33] op_sel_hi:[1,0,1]
	v_pk_fma_f32 v[60:61], v[30:31], v[20:21], v[34:35] op_sel_hi:[1,0,1]
	s_waitcnt lgkmcnt(7)
	v_pk_mul_f32 v[46:47], v[58:59], v[46:47] op_sel_hi:[0,1]
	v_pk_fma_f32 v[46:47], v[58:59], v[48:49], v[46:47] op_sel:[1,0,0] op_sel_hi:[1,1,1]
	v_pk_fma_f32 v[46:47], v[60:61], v[76:77], v[46:47] op_sel_hi:[0,1,1]
	v_pk_fma_f32 v[46:47], v[60:61], v[78:79], v[46:47] op_sel:[1,0,0] op_sel_hi:[1,1,1]
	v_pk_fma_f32 v[68:69], v[58:59], v[50:51], v[68:69]
	v_pk_fma_f32 v[70:71], v[60:61], v[52:53], v[70:71]
	v_add_f32_dpp v46, v46, v46 quad_perm:[1,0,3,2] row_mask:0xf bank_mask:0xf bound_ctrl:1
	ds_read_b128 v[20:23], v73 offset:12288
	ds_read_b128 v[36:39], v73 offset:12304
	v_add_f32_dpp v46, v46, v46 quad_perm:[2,3,0,1] row_mask:0xf bank_mask:0xf bound_ctrl:1
	ds_read_b128 v[24:27], v74 offset:12800
	ds_read_b128 v[32:35], v75 offset:12288
	v_add_f32_dpp v46, v46, v46 row_half_mirror row_mask:0xf bank_mask:0xf bound_ctrl:1
	ds_read_b128 v[28:31], v74 offset:13056
	ds_write_b32 v72, v47 offset:512
	v_add_f32_dpp v46, v46, v46 row_mirror row_mask:0xf bank_mask:0xf bound_ctrl:1
	v_pk_fma_f32 v[58:59], v[54:55], v[46:47], v[68:69] op_sel_hi:[1,0,1]
	v_pk_fma_f32 v[60:61], v[56:57], v[46:47], v[70:71] op_sel_hi:[1,0,1]
	s_waitcnt lgkmcnt(7)
	v_pk_mul_f32 v[0:1], v[58:59], v[0:1] op_sel_hi:[0,1]
	v_pk_fma_f32 v[0:1], v[58:59], v[2:3], v[0:1] op_sel:[1,0,0] op_sel_hi:[1,1,1]
	v_pk_fma_f32 v[0:1], v[60:61], v[16:17], v[0:1] op_sel_hi:[0,1,1]
	v_pk_fma_f32 v[0:1], v[60:61], v[18:19], v[0:1] op_sel:[1,0,0] op_sel_hi:[1,1,1]
	v_pk_fma_f32 v[12:13], v[58:59], v[4:5], v[12:13]
	v_pk_fma_f32 v[14:15], v[60:61], v[6:7], v[14:15]
	v_add_f32_dpp v0, v0, v0 quad_perm:[1,0,3,2] row_mask:0xf bank_mask:0xf bound_ctrl:1
	ds_read_b128 v[46:49], v73 offset:15360
	ds_read_b128 v[76:79], v73 offset:15376
	v_add_f32_dpp v0, v0, v0 quad_perm:[2,3,0,1] row_mask:0xf bank_mask:0xf bound_ctrl:1
	ds_read_b128 v[50:53], v74 offset:15872
	ds_read_b128 v[68:71], v75 offset:15360
	v_add_f32_dpp v0, v0, v0 row_half_mirror row_mask:0xf bank_mask:0xf bound_ctrl:1
	ds_read_b128 v[54:57], v74 offset:16128
	ds_write_b32 v72, v1 offset:1024
	v_add_f32_dpp v0, v0, v0 row_mirror row_mask:0xf bank_mask:0xf bound_ctrl:1
	v_pk_fma_f32 v[58:59], v[8:9], v[0:1], v[12:13] op_sel_hi:[1,0,1]
	v_pk_fma_f32 v[60:61], v[10:11], v[0:1], v[14:15] op_sel_hi:[1,0,1]
	s_waitcnt lgkmcnt(7)
; #define LAS __attribute__((address_space(3)))
; #define RW_LDS_WAIT(X) asm volatile("s_waitcnt lgkmcnt(0)" : "+v"(nk##X), "+v"(dd##X), "+v"(bb##X), "+v"(kp##X), "+v"(rr##X), "+v"(vv##X) :: "memory")
; DI void rwkv_scan_phase(int wv, const Params& P, LAS unsigned char* lds) {
;     ...
;                 f32x2 yacc = (f32x2){0.f, 0.f};
;                 unsigned sbt = sba, vbt = vba; LAS float* ybt = yb;
;                 RW_LDS_LOAD(A, 0); RW_LDS_WAIT(A);
; #pragma unroll 1
;                 for (int tt = 0; tt < RW_T; tt += 16) { sbt = sba + (unsigned)tt * 1280u; vbt = vba + (unsigned)tt * 32u; ybt = yb + tt * 128;
;                     RW_LDS_LOAD(B, 1); RW_STEP(A, 0); RW_LDS_WAIT(B);
;                     RW_LDS_LOAD(A, 2); RW_STEP(B, 1); RW_LDS_WAIT(A);
;                     RW_LDS_LOAD(B, 3); RW_STEP(A, 2); RW_LDS_WAIT(B);
;                     RW_LDS_LOAD(A, 4); RW_STEP(B, 3); RW_LDS_WAIT(A);
;                     RW_LDS_LOAD(B, 5); RW_STEP(A, 4); RW_LDS_WAIT(B);
;                     RW_LDS_LOAD(A, 6); RW_STEP(B, 5); RW_LDS_WAIT(A);
;                     RW_LDS_LOAD(B, 7); RW_STEP(A, 6); RW_LDS_WAIT(B);
;                     RW_LDS_LOAD(A, 8); RW_STEP(B, 7); RW_LDS_WAIT(A);
;                     RW_LDS_LOAD(B, 9); RW_STEP(A, 8); RW_LDS_WAIT(B);
;                     RW_LDS_LOAD(A, 10); RW_STEP(B, 9); RW_LDS_WAIT(A);
;                     RW_LDS_LOAD(B, 11); RW_STEP(A, 10); RW_LDS_WAIT(B);
;                     RW_LDS_LOAD(A, 12); RW_STEP(B, 11); RW_LDS_WAIT(A);
;                     RW_LDS_LOAD(B, 13); RW_STEP(A, 12); RW_LDS_WAIT(B);
;                     RW_LDS_LOAD(A, 14); RW_STEP(B, 13); RW_LDS_WAIT(A);
;                     RW_LDS_LOAD(B, 15); RW_STEP(A, 14); RW_LDS_WAIT(B);
;                     RW_LDS_LOAD(A, 16); RW_STEP(B, 15); RW_LDS_WAIT(A);
	v_pk_mul_f32 v[20:21], v[58:59], v[20:21] op_sel_hi:[0,1]
	v_pk_fma_f32 v[20:21], v[58:59], v[22:23], v[20:21] op_sel:[1,0,0] op_sel_hi:[1,1,1]
	v_pk_fma_f32 v[20:21], v[60:61], v[36:37], v[20:21] op_sel_hi:[0,1,1]
	v_pk_fma_f32 v[20:21], v[60:61], v[38:39], v[20:21] op_sel:[1,0,0] op_sel_hi:[1,1,1]
	v_pk_fma_f32 v[32:33], v[58:59], v[24:25], v[32:33]
	v_pk_fma_f32 v[34:35], v[60:61], v[26:27], v[34:35]
	v_add_f32_dpp v20, v20, v20 quad_perm:[1,0,3,2] row_mask:0xf bank_mask:0xf bound_ctrl:1
	ds_read_b128 v[0:3], v73 offset:18432
	ds_read_b128 v[16:19], v73 offset:18448
	v_add_f32_dpp v20, v20, v20 quad_perm:[2,3,0,1] row_mask:0xf bank_mask:0xf bound_ctrl:1
	ds_read_b128 v[4:7], v74 offset:18944
	ds_read_b128 v[12:15], v75 offset:18432
	v_add_f32_dpp v20, v20, v20 row_half_mirror row_mask:0xf bank_mask:0xf bound_ctrl:1
	ds_read_b128 v[8:11], v74 offset:19200
	ds_write_b32 v72, v21 offset:1536
	v_add_f32_dpp v20, v20, v20 row_mirror row_mask:0xf bank_mask:0xf bound_ctrl:1
	v_pk_fma_f32 v[58:59], v[28:29], v[20:21], v[32:33] op_sel_hi:[1,0,1]
	v_pk_fma_f32 v[60:61], v[30:31], v[20:21], v[34:35] op_sel_hi:[1,0,1]
	s_waitcnt lgkmcnt(7)
	v_pk_mul_f32 v[46:47], v[58:59], v[46:47] op_sel_hi:[0,1]
	v_pk_fma_f32 v[46:47], v[58:59], v[48:49], v[46:47] op_sel:[1,0,0] op_sel_hi:[1,1,1]
	v_pk_fma_f32 v[46:47], v[60:61], v[76:77], v[46:47] op_sel_hi:[0,1,1]
	v_pk_fma_f32 v[46:47], v[60:61], v[78:79], v[46:47] op_sel:[1,0,0] op_sel_hi:[1,1,1]
	v_pk_fma_f32 v[68:69], v[58:59], v[50:51], v[68:69]
	v_pk_fma_f32 v[70:71], v[60:61], v[52:53], v[70:71]
	v_add_f32_dpp v46, v46, v46 quad_perm:[1,0,3,2] row_mask:0xf bank_mask:0xf bound_ctrl:1
	ds_read_b128 v[20:23], v73 offset:21504
	ds_read_b128 v[36:39], v73 offset:21520
	v_add_f32_dpp v46, v46, v46 quad_perm:[2,3,0,1] row_mask:0xf bank_mask:0xf bound_ctrl:1
	ds_read_b128 v[24:27], v74 offset:22016
	ds_read_b128 v[32:35], v75 offset:21504
	v_add_f32_dpp v46, v46, v46 row_half_mirror row_mask:0xf bank_mask:0xf bound_ctrl:1
	ds_read_b128 v[28:31], v74 offset:22272
	ds_write_b32 v72, v47 offset:2048
	v_add_f32_dpp v46, v46, v46 row_mirror row_mask:0xf bank_mask:0xf bound_ctrl:1
	v_pk_fma_f32 v[58:59], v[54:55], v[46:47], v[68:69] op_sel_hi:[1,0,1]
	v_pk_fma_f32 v[60:61], v[56:57], v[46:47], v[70:71] op_sel_hi:[1,0,1]
	s_waitcnt lgkmcnt(7)
	v_pk_mul_f32 v[0:1], v[58:59], v[0:1] op_sel_hi:[0,1]
	v_pk_fma_f32 v[0:1], v[58:59], v[2:3], v[0:1] op_sel:[1,0,0] op_sel_hi:[1,1,1]
	v_pk_fma_f32 v[0:1], v[60:61], v[16:17], v[0:1] op_sel_hi:[0,1,1]
	v_pk_fma_f32 v[0:1], v[60:61], v[18:19], v[0:1] op_sel:[1,0,0] op_sel_hi:[1,1,1]
	v_pk_fma_f32 v[12:13], v[58:59], v[4:5], v[12:13]
	v_pk_fma_f32 v[14:15], v[60:61], v[6:7], v[14:15]
	v_add_f32_dpp v0, v0, v0 quad_perm:[1,0,3,2] row_mask:0xf bank_mask:0xf bound_ctrl:1
	ds_read_b128 v[46:49], v73 offset:24576
	ds_read_b128 v[76:79], v73 offset:24592
	v_add_f32_dpp v0, v0, v0 quad_perm:[2,3,0,1] row_mask:0xf bank_mask:0xf bound_ctrl:1
	ds_read_b128 v[50:53], v74 offset:25088
	ds_read_b128 v[68:71], v75 offset:24576
	v_add_f32_dpp v0, v0, v0 row_half_mirror row_mask:0xf bank_mask:0xf bound_ctrl:1
	ds_read_b128 v[54:57], v74 offset:25344
	ds_write_b32 v72, v1 offset:2560
	v_add_f32_dpp v0, v0, v0 row_mirror row_mask:0xf bank_mask:0xf bound_ctrl:1
	v_pk_fma_f32 v[58:59], v[8:9], v[0:1], v[12:13] op_sel_hi:[1,0,1]
	v_pk_fma_f32 v[60:61], v[10:11], v[0:1], v[14:15] op_sel_hi:[1,0,1]
	s_waitcnt lgkmcnt(7)
	v_pk_mul_f32 v[20:21], v[58:59], v[20:21] op_sel_hi:[0,1]
	v_pk_fma_f32 v[20:21], v[58:59], v[22:23], v[20:21] op_sel:[1,0,0] op_sel_hi:[1,1,1]
	v_pk_fma_f32 v[20:21], v[60:61], v[36:37], v[20:21] op_sel_hi:[0,1,1]
	v_pk_fma_f32 v[20:21], v[60:61], v[38:39], v[20:21] op_sel:[1,0,0] op_sel_hi:[1,1,1]
	v_pk_fma_f32 v[32:33], v[58:59], v[24:25], v[32:33]
	v_pk_fma_f32 v[34:35], v[60:61], v[26:27], v[34:35]
	v_add_f32_dpp v20, v20, v20 quad_perm:[1,0,3,2] row_mask:0xf bank_mask:0xf bound_ctrl:1
	ds_read_b128 v[0:3], v73 offset:27648
	ds_read_b128 v[16:19], v73 offset:27664
	v_add_f32_dpp v20, v20, v20 quad_perm:[2,3,0,1] row_mask:0xf bank_mask:0xf bound_ctrl:1
	ds_read_b128 v[4:7], v74 offset:28160
	ds_read_b128 v[12:15], v75 offset:27648
	v_add_f32_dpp v20, v20, v20 row_half_mirror row_mask:0xf bank_mask:0xf bound_ctrl:1
	ds_read_b128 v[8:11], v74 offset:28416
	ds_write_b32 v72, v21 offset:3072
	v_add_f32_dpp v20, v20, v20 row_mirror row_mask:0xf bank_mask:0xf bound_ctrl:1
	v_pk_fma_f32 v[58:59], v[28:29], v[20:21], v[32:33] op_sel_hi:[1,0,1]
	v_pk_fma_f32 v[60:61], v[30:31], v[20:21], v[34:35] op_sel_hi:[1,0,1]
	s_waitcnt lgkmcnt(7)
	v_pk_mul_f32 v[46:47], v[58:59], v[46:47] op_sel_hi:[0,1]
	v_pk_fma_f32 v[46:47], v[58:59], v[48:49], v[46:47] op_sel:[1,0,0] op_sel_hi:[1,1,1]
	v_pk_fma_f32 v[46:47], v[60:61], v[76:77], v[46:47] op_sel_hi:[0,1,1]
	v_pk_fma_f32 v[46:47], v[60:61], v[78:79], v[46:47] op_sel:[1,0,0] op_sel_hi:[1,1,1]
	v_pk_fma_f32 v[68:69], v[58:59], v[50:51], v[68:69]
	v_pk_fma_f32 v[70:71], v[60:61], v[52:53], v[70:71]
	v_add_f32_dpp v46, v46, v46 quad_perm:[1,0,3,2] row_mask:0xf bank_mask:0xf bound_ctrl:1
	ds_read_b128 v[20:23], v73 offset:30720
	ds_read_b128 v[36:39], v73 offset:30736
	v_add_f32_dpp v46, v46, v46 quad_perm:[2,3,0,1] row_mask:0xf bank_mask:0xf bound_ctrl:1
	ds_read_b128 v[24:27], v74 offset:31232
	ds_read_b128 v[32:35], v75 offset:30720
	v_add_f32_dpp v46, v46, v46 row_half_mirror row_mask:0xf bank_mask:0xf bound_ctrl:1
	ds_read_b128 v[28:31], v74 offset:31488
	ds_write_b32 v72, v47 offset:3584
	v_add_f32_dpp v46, v46, v46 row_mirror row_mask:0xf bank_mask:0xf bound_ctrl:1
	v_pk_fma_f32 v[58:59], v[54:55], v[46:47], v[68:69] op_sel_hi:[1,0,1]
	v_pk_fma_f32 v[60:61], v[56:57], v[46:47], v[70:71] op_sel_hi:[1,0,1]
	s_waitcnt lgkmcnt(7)
; #define LAS __attribute__((address_space(3)))
; #define RW_LDS_WAIT(X) asm volatile("s_waitcnt lgkmcnt(0)" : "+v"(nk##X), "+v"(dd##X), "+v"(bb##X), "+v"(kp##X), "+v"(rr##X), "+v"(vv##X) :: "memory")
; DI void rwkv_scan_phase(int wv, const Params& P, LAS unsigned char* lds) {
;     ...
;                 f32x2 yacc = (f32x2){0.f, 0.f};
;                 unsigned sbt = sba, vbt = vba; LAS float* ybt = yb;
;                 RW_LDS_LOAD(A, 0); RW_LDS_WAIT(A);
; #pragma unroll 1
;                 for (int tt = 0; tt < RW_T; tt += 16) { sbt = sba + (unsigned)tt * 1280u; vbt = vba + (unsigned)tt * 32u; ybt = yb + tt * 128;
;                     RW_LDS_LOAD(B, 1); RW_STEP(A, 0); RW_LDS_WAIT(B);
;                     RW_LDS_LOAD(A, 2); RW_STEP(B, 1); RW_LDS_WAIT(A);
;                     RW_LDS_LOAD(B, 3); RW_STEP(A, 2); RW_LDS_WAIT(B);
;                     RW_LDS_LOAD(A, 4); RW_STEP(B, 3); RW_LDS_WAIT(A);
;                     RW_LDS_LOAD(B, 5); RW_STEP(A, 4); RW_LDS_WAIT(B);
;                     RW_LDS_LOAD(A, 6); RW_STEP(B, 5); RW_LDS_WAIT(A);
;                     RW_LDS_LOAD(B, 7); RW_STEP(A, 6); RW_LDS_WAIT(B);
;                     RW_LDS_LOAD(A, 8); RW_STEP(B, 7); RW_LDS_WAIT(A);
;                     RW_LDS_LOAD(B, 9); RW_STEP(A, 8); RW_LDS_WAIT(B);
;                     RW_LDS_LOAD(A, 10); RW_STEP(B, 9); RW_LDS_WAIT(A);
;                     RW_LDS_LOAD(B, 11); RW_STEP(A, 10); RW_LDS_WAIT(B);
;                     RW_LDS_LOAD(A, 12); RW_STEP(B, 11); RW_LDS_WAIT(A);
;                     RW_LDS_LOAD(B, 13); RW_STEP(A, 12); RW_LDS_WAIT(B);
;                     RW_LDS_LOAD(A, 14); RW_STEP(B, 13); RW_LDS_WAIT(A);
;                     RW_LDS_LOAD(B, 15); RW_STEP(A, 14); RW_LDS_WAIT(B);
;                     RW_LDS_LOAD(A, 16); RW_STEP(B, 15); RW_LDS_WAIT(A);
;                 }
;                 yb[(RW_T - 1) * 128] = yacc[0] + yacc[1];
;     ...
;                 __syncthreads();
	v_pk_mul_f32 v[0:1], v[58:59], v[0:1] op_sel_hi:[0,1]
	v_pk_fma_f32 v[0:1], v[58:59], v[2:3], v[0:1] op_sel:[1,0,0] op_sel_hi:[1,1,1]
	v_pk_fma_f32 v[0:1], v[60:61], v[16:17], v[0:1] op_sel_hi:[0,1,1]
	v_pk_fma_f32 v[0:1], v[60:61], v[18:19], v[0:1] op_sel:[1,0,0] op_sel_hi:[1,1,1]
	v_pk_fma_f32 v[12:13], v[58:59], v[4:5], v[12:13]
	v_pk_fma_f32 v[14:15], v[60:61], v[6:7], v[14:15]
	v_add_f32_dpp v0, v0, v0 quad_perm:[1,0,3,2] row_mask:0xf bank_mask:0xf bound_ctrl:1
	ds_read_b128 v[46:49], v73 offset:33792
	ds_read_b128 v[76:79], v73 offset:33808
	v_add_f32_dpp v0, v0, v0 quad_perm:[2,3,0,1] row_mask:0xf bank_mask:0xf bound_ctrl:1
	ds_read_b128 v[50:53], v74 offset:34304
	ds_read_b128 v[68:71], v75 offset:33792
	v_add_f32_dpp v0, v0, v0 row_half_mirror row_mask:0xf bank_mask:0xf bound_ctrl:1
	ds_read_b128 v[54:57], v74 offset:34560
	ds_write_b32 v72, v1 offset:4096
	v_add_f32_dpp v0, v0, v0 row_mirror row_mask:0xf bank_mask:0xf bound_ctrl:1
	v_pk_fma_f32 v[58:59], v[8:9], v[0:1], v[12:13] op_sel_hi:[1,0,1]
	v_pk_fma_f32 v[60:61], v[10:11], v[0:1], v[14:15] op_sel_hi:[1,0,1]
	s_waitcnt lgkmcnt(7)
	v_pk_mul_f32 v[20:21], v[58:59], v[20:21] op_sel_hi:[0,1]
	v_pk_fma_f32 v[20:21], v[58:59], v[22:23], v[20:21] op_sel:[1,0,0] op_sel_hi:[1,1,1]
	v_pk_fma_f32 v[20:21], v[60:61], v[36:37], v[20:21] op_sel_hi:[0,1,1]
	v_pk_fma_f32 v[20:21], v[60:61], v[38:39], v[20:21] op_sel:[1,0,0] op_sel_hi:[1,1,1]
	v_pk_fma_f32 v[32:33], v[58:59], v[24:25], v[32:33]
	v_pk_fma_f32 v[34:35], v[60:61], v[26:27], v[34:35]
	v_add_f32_dpp v20, v20, v20 quad_perm:[1,0,3,2] row_mask:0xf bank_mask:0xf bound_ctrl:1
	ds_read_b128 v[0:3], v73 offset:36864
	ds_read_b128 v[16:19], v73 offset:36880
	v_add_f32_dpp v20, v20, v20 quad_perm:[2,3,0,1] row_mask:0xf bank_mask:0xf bound_ctrl:1
	ds_read_b128 v[4:7], v74 offset:37376
	ds_read_b128 v[12:15], v75 offset:36864
	v_add_f32_dpp v20, v20, v20 row_half_mirror row_mask:0xf bank_mask:0xf bound_ctrl:1
	ds_read_b128 v[8:11], v74 offset:37632
	ds_write_b32 v72, v21 offset:4608
	v_add_f32_dpp v20, v20, v20 row_mirror row_mask:0xf bank_mask:0xf bound_ctrl:1
	v_pk_fma_f32 v[58:59], v[28:29], v[20:21], v[32:33] op_sel_hi:[1,0,1]
	v_pk_fma_f32 v[60:61], v[30:31], v[20:21], v[34:35] op_sel_hi:[1,0,1]
	s_waitcnt lgkmcnt(7)
	v_pk_mul_f32 v[46:47], v[58:59], v[46:47] op_sel_hi:[0,1]
	v_pk_fma_f32 v[46:47], v[58:59], v[48:49], v[46:47] op_sel:[1,0,0] op_sel_hi:[1,1,1]
	v_pk_fma_f32 v[46:47], v[60:61], v[76:77], v[46:47] op_sel_hi:[0,1,1]
	v_pk_fma_f32 v[46:47], v[60:61], v[78:79], v[46:47] op_sel:[1,0,0] op_sel_hi:[1,1,1]
	v_pk_fma_f32 v[68:69], v[58:59], v[50:51], v[68:69]
	v_pk_fma_f32 v[70:71], v[60:61], v[52:53], v[70:71]
	v_add_f32_dpp v46, v46, v46 quad_perm:[1,0,3,2] row_mask:0xf bank_mask:0xf bound_ctrl:1
	ds_read_b128 v[20:23], v73 offset:39936
	ds_read_b128 v[36:39], v73 offset:39952
	v_add_f32_dpp v46, v46, v46 quad_perm:[2,3,0,1] row_mask:0xf bank_mask:0xf bound_ctrl:1
	ds_read_b128 v[24:27], v74 offset:40448
	ds_read_b128 v[32:35], v75 offset:39936
	v_add_f32_dpp v46, v46, v46 row_half_mirror row_mask:0xf bank_mask:0xf bound_ctrl:1
	ds_read_b128 v[28:31], v74 offset:40704
	ds_write_b32 v72, v47 offset:5120
	v_add_f32_dpp v46, v46, v46 row_mirror row_mask:0xf bank_mask:0xf bound_ctrl:1
	v_pk_fma_f32 v[58:59], v[54:55], v[46:47], v[68:69] op_sel_hi:[1,0,1]
	v_pk_fma_f32 v[60:61], v[56:57], v[46:47], v[70:71] op_sel_hi:[1,0,1]
	s_waitcnt lgkmcnt(7)
	v_pk_mul_f32 v[0:1], v[58:59], v[0:1] op_sel_hi:[0,1]
	v_pk_fma_f32 v[0:1], v[58:59], v[2:3], v[0:1] op_sel:[1,0,0] op_sel_hi:[1,1,1]
	v_pk_fma_f32 v[0:1], v[60:61], v[16:17], v[0:1] op_sel_hi:[0,1,1]
	v_pk_fma_f32 v[0:1], v[60:61], v[18:19], v[0:1] op_sel:[1,0,0] op_sel_hi:[1,1,1]
	v_pk_fma_f32 v[12:13], v[58:59], v[4:5], v[12:13]
	v_pk_fma_f32 v[14:15], v[60:61], v[6:7], v[14:15]
	v_add_f32_dpp v0, v0, v0 quad_perm:[1,0,3,2] row_mask:0xf bank_mask:0xf bound_ctrl:1
	ds_read_b128 v[46:49], v73 offset:43008
	ds_read_b128 v[76:79], v73 offset:43024
	v_add_f32_dpp v0, v0, v0 quad_perm:[2,3,0,1] row_mask:0xf bank_mask:0xf bound_ctrl:1
	ds_read_b128 v[50:53], v74 offset:43520
	ds_read_b128 v[68:71], v75 offset:43008
	v_add_f32_dpp v0, v0, v0 row_half_mirror row_mask:0xf bank_mask:0xf bound_ctrl:1
	ds_read_b128 v[54:57], v74 offset:43776
	ds_write_b32 v72, v1 offset:5632
	v_add_f32_dpp v0, v0, v0 row_mirror row_mask:0xf bank_mask:0xf bound_ctrl:1
	v_pk_fma_f32 v[58:59], v[8:9], v[0:1], v[12:13] op_sel_hi:[1,0,1]
	v_pk_fma_f32 v[60:61], v[10:11], v[0:1], v[14:15] op_sel_hi:[1,0,1]
	s_waitcnt lgkmcnt(7)
	v_pk_mul_f32 v[20:21], v[58:59], v[20:21] op_sel_hi:[0,1]
	v_pk_fma_f32 v[20:21], v[58:59], v[22:23], v[20:21] op_sel:[1,0,0] op_sel_hi:[1,1,1]
	v_pk_fma_f32 v[20:21], v[60:61], v[36:37], v[20:21] op_sel_hi:[0,1,1]
	v_pk_fma_f32 v[20:21], v[60:61], v[38:39], v[20:21] op_sel:[1,0,0] op_sel_hi:[1,1,1]
	v_pk_fma_f32 v[32:33], v[58:59], v[24:25], v[32:33]
	v_pk_fma_f32 v[34:35], v[60:61], v[26:27], v[34:35]
	v_add_f32_dpp v20, v20, v20 quad_perm:[1,0,3,2] row_mask:0xf bank_mask:0xf bound_ctrl:1
	ds_read_b128 v[0:3], v73 offset:46080
	ds_read_b128 v[16:19], v73 offset:46096
	v_add_f32_dpp v20, v20, v20 quad_perm:[2,3,0,1] row_mask:0xf bank_mask:0xf bound_ctrl:1
	ds_read_b128 v[4:7], v74 offset:46592
	ds_read_b128 v[12:15], v75 offset:46080
	v_add_f32_dpp v20, v20, v20 row_half_mirror row_mask:0xf bank_mask:0xf bound_ctrl:1
	ds_read_b128 v[8:11], v74 offset:46848
	ds_write_b32 v72, v21 offset:6144
	v_add_f32_dpp v20, v20, v20 row_mirror row_mask:0xf bank_mask:0xf bound_ctrl:1
	v_pk_fma_f32 v[58:59], v[28:29], v[20:21], v[32:33] op_sel_hi:[1,0,1]
	v_pk_fma_f32 v[60:61], v[30:31], v[20:21], v[34:35] op_sel_hi:[1,0,1]
	s_waitcnt lgkmcnt(7)
	v_pk_mul_f32 v[46:47], v[58:59], v[46:47] op_sel_hi:[0,1]
	v_pk_fma_f32 v[46:47], v[58:59], v[48:49], v[46:47] op_sel:[1,0,0] op_sel_hi:[1,1,1]
	v_pk_fma_f32 v[46:47], v[60:61], v[76:77], v[46:47] op_sel_hi:[0,1,1]
	v_pk_fma_f32 v[46:47], v[60:61], v[78:79], v[46:47] op_sel:[1,0,0] op_sel_hi:[1,1,1]
	v_pk_fma_f32 v[68:69], v[58:59], v[50:51], v[68:69]
	v_pk_fma_f32 v[70:71], v[60:61], v[52:53], v[70:71]
	v_add_f32_dpp v46, v46, v46 quad_perm:[1,0,3,2] row_mask:0xf bank_mask:0xf bound_ctrl:1
	s_add_i32 s47, s47, 1
	ds_write_b32 v72, v47 offset:6656
	v_add_f32_dpp v46, v46, v46 quad_perm:[2,3,0,1] row_mask:0xf bank_mask:0xf bound_ctrl:1
	s_add_i32 s42, s42, 0x2000
	s_cmp_eq_u32 s42, 0x6000
	v_add_f32_dpp v46, v46, v46 row_half_mirror row_mask:0xf bank_mask:0xf bound_ctrl:1
	s_cselect_b32 s42, 0, s42
	s_lshl_b32 s40, s47, 4
	v_add_f32_dpp v46, v46, v46 row_mirror row_mask:0xf bank_mask:0xf bound_ctrl:1
	v_pk_fma_f32 v[58:59], v[54:55], v[46:47], v[68:69] op_sel_hi:[1,0,1]
	v_pk_fma_f32 v[60:61], v[56:57], v[46:47], v[70:71] op_sel_hi:[1,0,1]
	s_waitcnt lgkmcnt(0)
	s_barrier
; #define LAS __attribute__((address_space(3)))
; #define RW_LDS_WAIT(X) asm volatile("s_waitcnt lgkmcnt(0)" : "+v"(nk##X), "+v"(dd##X), "+v"(bb##X), "+v"(kp##X), "+v"(rr##X), "+v"(vv##X) :: "memory")
; DI void rwkv_scan_phase(int wv, const Params& P, LAS unsigned char* lds) {
;     ...
;                 f32x2 yacc = (f32x2){0.f, 0.f};
;                 unsigned sbt = sba, vbt = vba; LAS float* ybt = yb;
;                 RW_LDS_LOAD(A, 0); RW_LDS_WAIT(A);
; #pragma unroll 1
;                 for (int tt = 0; tt < RW_T; tt += 16) { sbt = sba + (unsigned)tt * 1280u; vbt = vba + (unsigned)tt * 32u; ybt = yb + tt * 128;
;                     RW_LDS_LOAD(B, 1); RW_STEP(A, 0); RW_LDS_WAIT(B);
;                     RW_LDS_LOAD(A, 2); RW_STEP(B, 1); RW_LDS_WAIT(A);
;                     RW_LDS_LOAD(B, 3); RW_STEP(A, 2); RW_LDS_WAIT(B);
;                     RW_LDS_LOAD(A, 4); RW_STEP(B, 3); RW_LDS_WAIT(A);
;                     RW_LDS_LOAD(B, 5); RW_STEP(A, 4); RW_LDS_WAIT(B);
;                     RW_LDS_LOAD(A, 6); RW_STEP(B, 5); RW_LDS_WAIT(A);
;                     RW_LDS_LOAD(B, 7); RW_STEP(A, 6); RW_LDS_WAIT(B);
;                     RW_LDS_LOAD(A, 8); RW_STEP(B, 7); RW_LDS_WAIT(A);
;                     RW_LDS_LOAD(B, 9); RW_STEP(A, 8); RW_LDS_WAIT(B);
;                     RW_LDS_LOAD(A, 10); RW_STEP(B, 9); RW_LDS_WAIT(A);
;                     RW_LDS_LOAD(B, 11); RW_STEP(A, 10); RW_LDS_WAIT(B);
;                     RW_LDS_LOAD(A, 12); RW_STEP(B, 11); RW_LDS_WAIT(A);
;                     RW_LDS_LOAD(B, 13); RW_STEP(A, 12); RW_LDS_WAIT(B);
;                     RW_LDS_LOAD(A, 14); RW_STEP(B, 13); RW_LDS_WAIT(A);
;                     RW_LDS_LOAD(B, 15); RW_STEP(A, 14); RW_LDS_WAIT(B);
;                     RW_LDS_LOAD(A, 16); RW_STEP(B, 15); RW_LDS_WAIT(A);
;                 }
;                 yb[(RW_T - 1) * 128] = yacc[0] + yacc[1];
;     ...
;                 __syncthreads();
	v_pk_mul_f32 v[0:1], v[58:59], v[0:1] op_sel_hi:[0,1]
	v_pk_fma_f32 v[0:1], v[58:59], v[2:3], v[0:1] op_sel:[1,0,0] op_sel_hi:[1,1,1]
	v_pk_fma_f32 v[0:1], v[60:61], v[16:17], v[0:1] op_sel_hi:[0,1,1]
	v_pk_fma_f32 v[0:1], v[60:61], v[18:19], v[0:1] op_sel:[1,0,0] op_sel_hi:[1,1,1]
	v_pk_fma_f32 v[12:13], v[58:59], v[4:5], v[12:13]
	v_pk_fma_f32 v[14:15], v[60:61], v[6:7], v[14:15]
	v_add_f32_dpp v0, v0, v0 quad_perm:[1,0,3,2] row_mask:0xf bank_mask:0xf bound_ctrl:1
	ds_write_b32 v72, v1 offset:7168
	s_and_b32 s40, s40, 16
	v_add_f32_dpp v0, v0, v0 quad_perm:[2,3,0,1] row_mask:0xf bank_mask:0xf bound_ctrl:1
	s_mul_i32 s41, s40, 0xc00
	v_add_u32_e32 v74, s41, v45
	v_add_f32_dpp v0, v0, v0 row_half_mirror row_mask:0xf bank_mask:0xf bound_ctrl:1
	v_add_u32_e32 v73, v74, v45
	v_add_u32_e32 v75, s41, v42
	v_add_f32_dpp v0, v0, v0 row_mirror row_mask:0xf bank_mask:0xf bound_ctrl:1
	v_pk_fma_f32 v[58:59], v[8:9], v[0:1], v[12:13] op_sel_hi:[1,0,1]
	v_pk_fma_f32 v[60:61], v[10:11], v[0:1], v[14:15] op_sel_hi:[1,0,1]
	v_add_u32_e32 v67, s42, v62
	s_lshl_b32 s41, s40, 4
	s_add_i32 s41, s41, 0x1e000
	v_add_u32_e32 v40, s41, v45
	s_cmpk_eq_i32 s47, 0x200
	ds_read_b128 v[0:3], v73
	ds_read_b128 v[16:19], v73 offset:16
	ds_read_b128 v[4:7], v74 offset:512
	ds_read_b128 v[12:15], v75
	ds_read_b128 v[8:11], v74 offset:768
	ds_read_b128 v[20:23], v73 offset:3072
	ds_read_b128 v[36:39], v73 offset:3088
	ds_read_b128 v[24:27], v74 offset:3584
	ds_read_b128 v[32:35], v75 offset:3072
	ds_read_b128 v[28:31], v74 offset:3840
	s_cbranch_scc0 .Lscan_chunk
	v_add_u32_e32 v40, 0x1e100, v45
	ds_read_b128 v[20:23], v40
	s_waitcnt lgkmcnt(0)
	v_pk_mul_f32 v[64:65], v[20:21], v[58:59]
	v_pk_fma_f32 v[64:65], v[22:23], v[60:61], v[64:65]
	s_nop 0
	v_add_f32_e32 v64, v64, v65
	ds_write_b32 v72, v64 offset:7680
	s_waitcnt lgkmcnt(0)
	s_barrier
